# attention: next step's K-fragment ds_reads issued right behind the step barrier (bf16 converts overlap the LDS latency); unrolled bodies expect them in flight
# baseline (speedup 1.0000x reference)
; template <bool FIRST, bool HAS_PREV> ...
;     ...
;     { const float nm = FIRST ? 0.f : -st.mrun;
; #pragma unroll
;       for (int i = 0; i < 16; ++i) { c0[i] = nm; c1[i] = nm; } }
; #pragma unroll
;     for (int ks = 0; ks < 2; ++ks) { DSR128(kf[2 * ks], ka[ks], 0); DSR128(kf[2 * ks + 1], ka[ks], 4096); }
;     asm volatile("s_waitcnt lgkmcnt(0)" : "+v"(kf[0]), "+v"(kf[1]), "+v"(kf[2]), "+v"(kf[3]));
; #pragma unroll
;     for (int ks = 0; ks < 2; ++ks) {
;         c0 = __builtin_amdgcn_mfma_f32_32x32x16_bf16(kf[2 * ks], qr[ks], c0, 0, 0, 0);
;         c1 = __builtin_amdgcn_mfma_f32_32x32x16_bf16(kf[2 * ks + 1], qr[ks], c1, 0, 0, 0);
;     }
;     __builtin_amdgcn_sched_barrier(0);
;     { bf16x8 kg[4];
; #pragma unroll
;       for (int ks = 0; ks < 2; ++ks) { DSR128(kg[2 * ks], ka[2 + ks], 0); DSR128(kg[2 * ks + 1], ka[2 + ks], 4096); }
;       asm volatile("s_waitcnt lgkmcnt(0)" : "+v"(kg[0]), "+v"(kg[1]), "+v"(kg[2]), "+v"(kg[3]));
; #pragma unroll
;       for (int ks = 0; ks < 2; ++ks) {
;           c0 = __builtin_amdgcn_mfma_f32_32x32x16_bf16(kg[2 * ks], qr[2 + ks], c0, 0, 0, 0);
; __device__ __forceinline__ void attn_unit(LAS unsigned char* lds, const bf16* __restrict__ Qb, const bf16* __restrict__ Kb, const bf16* __restrict__ VT, bf16* __restrict__ Y,
;                                           const float* __restrict__ gsub, float lam, int b, int h, int qb, float* o1scr) {
;     ...
;         const int c1 = 256 * (h >> 1) + 32 * (2 * (h & 1) + mp);
;         const bf16* qp = Qb + (tok0 + (size_t)qb * 256 + wid * 32 + r32) * 512 + c1 + 8 * hi;
;         bf16x8 qr[4];
;         qr[0] = *(const bf16x8*)(qp); qr[1] = *(const bf16x8*)(qp + 16); qr[2] = *(const bf16x8*)(qp + 128); qr[3] = *(const bf16x8*)(qp + 144);
;         const bf16* kp = Kb + (tok0 + lrow) * 512 + c1 + kcol;
;         const bf16* vp = VT + ((size_t)((b * 4 + h) * 32) * 128 + lrow) * 64 + lc * 8;
;         ATT_DMA(kp, 0); ATT_DMA(vp, VB0); ATT_DMA(vp + 4096, VB0 + 8192); ATT_DMA(kp + (size_t)64 * 512, KSL);
;         ATT_WAITBAR(0);
; #pragma unroll
;         for (int e = 0; e < 4; ++e)
; #pragma unroll
;             for (int i = 0; i < 16; ++i) o[e][i] = 0.f;
;         AttnState st; st.mrun = 0.f; st.l = 0.f;
;         bf16x8 pbp[4];
;         f32x16 sA, sB;
;         int s0 = 0, s1 = 1, s2 = 2;
;     ...
;         ATT_STEP(0, true, false);
.LBB0_560:
	s_or_b32 s44, s73, s44
	s_lshl_b64 s[82:83], s[44:45], 1
	v_lshl_add_u64 v[0:1], v[176:177], 0, s[82:83]
	global_load_dwordx4 v[96:99], v[0:1], off
	s_mov_b32 m0, s33
	v_lshl_add_u64 v[2:3], v[180:181], 0, s[82:83]
	global_load_dwordx4 v[100:103], v[0:1], off offset:32
	global_load_dwordx4 v[104:107], v[0:1], off offset:256
	global_load_dwordx4 v[108:111], v[0:1], off offset:288
	v_lshl_add_u64 v[0:1], v[2:3], 0, s[62:63]
	global_load_lds_dwordx4 v[2:3], off
	s_mov_b32 m0, s89
	v_lshl_add_u64 v[2:3], v[2:3], 0, s[64:65]
	global_load_lds_dwordx4 v[184:185], off
	s_mov_b32 m0, s90
	s_mov_b32 s44, s45
	global_load_lds_dwordx4 v[186:187], off
	s_mov_b32 m0, s91
	s_mov_b32 s46, s45
	global_load_lds_dwordx4 v[0:1], off
	s_waitcnt vmcnt(0) lgkmcnt(0)
	s_barrier
	s_mov_b32 m0, s92
	s_mov_b32 s47, s45
	global_load_lds_dwordx4 v[2:3], off
	s_mov_b32 m0, s93
	s_mov_b32 s48, s45
	global_load_lds_dwordx4 v[188:189], off
	s_mov_b32 m0, s94
	s_mov_b32 s49, s45
	global_load_lds_dwordx4 v[190:191], off
	ds_read_b128 v[0:3], v217 offset:0
	ds_read_b128 v[4:7], v217 offset:0x1000
	ds_read_b128 v[8:11], v218 offset:0
	ds_read_b128 v[48:51], v218 offset:0x1000
	s_mov_b32 s50, s45
	s_waitcnt lgkmcnt(0)
	s_mov_b32 s51, s45
	s_mov_b32 s52, s45
	s_mov_b32 s53, s45
	s_mov_b32 s54, s45
	s_mov_b32 s55, s45
	s_mov_b32 s56, s45
	s_mov_b32 s57, s45
	s_mov_b32 s58, s45
	s_mov_b32 s59, s45
	s_mov_b32 s74, 1
	s_waitcnt vmcnt(3)
	v_mfma_f32_32x32x16_bf16 v[16:31], v[0:3], v[96:99], 0
	v_mfma_f32_32x32x16_bf16 v[32:47], v[4:7], v[96:99], 0
	v_mfma_f32_32x32x16_bf16 v[16:31], v[8:11], v[100:103], v[16:31]
	v_mov_b64_e32 v[0:1], s[44:45]
	v_mov_b64_e32 v[2:3], s[46:47]
	v_mov_b64_e32 v[4:5], s[48:49]
	v_mov_b64_e32 v[6:7], s[50:51]
	v_mov_b64_e32 v[8:9], s[52:53]
	v_mov_b64_e32 v[10:11], s[54:55]
	v_mov_b64_e32 v[12:13], s[56:57]
	v_mfma_f32_32x32x16_bf16 v[32:47], v[48:51], v[100:103], v[32:47]
	v_mov_b64_e32 v[14:15], s[58:59]
	ds_read_b128 v[48:51], v219 offset:0
	ds_read_b128 v[52:55], v219 offset:0x1000
	ds_read_b128 v[56:59], v220 offset:0
	ds_read_b128 v[60:63], v220 offset:0x1000
	s_nop 0
	s_waitcnt lgkmcnt(0)
	s_nop 0
	v_mfma_f32_32x32x16_bf16 v[16:31], v[48:51], v[104:107], v[16:31]
	v_mfma_f32_32x32x16_bf16 v[32:47], v[52:55], v[104:107], v[32:47]
	v_mfma_f32_32x32x16_bf16 v[16:31], v[56:59], v[108:111], v[16:31]
	v_mfma_f32_32x32x16_bf16 v[32:47], v[60:63], v[108:111], v[32:47]
	s_nop 11
	v_max_f32_e32 v48, v33, v33
	v_max_f32_e32 v49, v17, v17
	v_max_f32_e32 v48, v49, v48
	v_max_f32_e32 v49, v34, v34
	v_max_f32_e32 v50, v18, v18
	v_max_f32_e32 v49, v50, v49
	v_max_f32_e32 v50, v35, v35
	v_max_f32_e32 v51, v19, v19
	v_max3_f32 v48, v16, v32, v48
	v_max_f32_e32 v50, v51, v50
	v_max3_f32 v48, v48, v49, v50
	v_max_f32_e32 v49, v36, v36
	v_max_f32_e32 v50, v20, v20
	v_max_f32_e32 v49, v50, v49
	v_max_f32_e32 v50, v37, v37
	v_max_f32_e32 v51, v21, v21
	v_max_f32_e32 v50, v51, v50
	v_max3_f32 v48, v48, v49, v50
	v_max_f32_e32 v49, v38, v38
	v_max_f32_e32 v50, v22, v22
	v_max_f32_e32 v49, v50, v49
	v_max_f32_e32 v50, v39, v39
	v_max_f32_e32 v51, v23, v23
	v_max_f32_e32 v50, v51, v50
	v_max3_f32 v48, v48, v49, v50
	v_max_f32_e32 v49, v40, v40
	v_max_f32_e32 v50, v24, v24
	v_max_f32_e32 v49, v50, v49
	v_max_f32_e32 v50, v41, v41
	v_max_f32_e32 v51, v25, v25
	v_max_f32_e32 v50, v51, v50
	v_max3_f32 v48, v48, v49, v50
	v_max_f32_e32 v49, v42, v42
	v_max_f32_e32 v50, v26, v26
	v_max_f32_e32 v49, v50, v49
	v_max_f32_e32 v50, v43, v43
	v_max_f32_e32 v51, v27, v27
	v_max_f32_e32 v50, v51, v50
	v_max3_f32 v48, v48, v49, v50
	v_max_f32_e32 v49, v44, v44
	v_max_f32_e32 v50, v28, v28
	v_max_f32_e32 v49, v50, v49
	v_max_f32_e32 v50, v45, v45
	v_max_f32_e32 v51, v29, v29
	v_max_f32_e32 v50, v51, v50
	v_max3_f32 v48, v48, v49, v50
	v_max_f32_e32 v49, v46, v46
	v_max_f32_e32 v50, v30, v30
	v_max_f32_e32 v49, v50, v49
	v_max_f32_e32 v50, v47, v47
	v_max_f32_e32 v51, v31, v31
	v_max_f32_e32 v50, v51, v50
	v_max3_f32 v48, v48, v49, v50
	v_mov_b32_e32 v49, v48
	s_nop 1
	v_permlane32_swap_b32_e32 v48, v49
	v_max_f32_e32 v49, v49, v49
	v_max_f32_e32 v48, v48, v48
	v_max_f32_e32 v49, v48, v49
	v_sub_f32_e32 v16, v16, v49
	v_sub_f32_e32 v32, v32, v49
	v_exp_f32_e32 v16, v16
	v_sub_f32_e32 v17, v17, v49
	v_exp_f32_e32 v32, v32
	v_sub_f32_e32 v33, v33, v49
	v_exp_f32_e32 v17, v17
	v_sub_f32_e32 v18, v18, v49
	v_exp_f32_e32 v33, v33
	v_sub_f32_e32 v34, v34, v49
	v_add_f32_e32 v48, 0, v16
	v_exp_f32_e32 v18, v18
	v_sub_f32_e32 v19, v19, v49
	v_add_f32_e32 v48, v32, v48
	v_exp_f32_e32 v34, v34
	v_sub_f32_e32 v35, v35, v49
	v_add_f32_e32 v48, v17, v48
	v_exp_f32_e32 v19, v19
	v_sub_f32_e32 v20, v20, v49
	v_add_f32_e32 v48, v33, v48
	v_exp_f32_e32 v35, v35
	v_sub_f32_e32 v36, v36, v49
	v_add_f32_e32 v48, v18, v48
	v_exp_f32_e32 v20, v20
	v_sub_f32_e32 v21, v21, v49
	v_add_f32_e32 v48, v34, v48
	v_exp_f32_e32 v36, v36
	v_sub_f32_e32 v37, v37, v49
	v_add_f32_e32 v48, v19, v48
	v_exp_f32_e32 v21, v21
	v_sub_f32_e32 v22, v22, v49
	v_add_f32_e32 v48, v35, v48
	v_exp_f32_e32 v37, v37
	v_sub_f32_e32 v38, v38, v49
	v_add_f32_e32 v48, v20, v48
	v_exp_f32_e32 v22, v22
	v_sub_f32_e32 v23, v23, v49
	v_add_f32_e32 v48, v36, v48
	v_exp_f32_e32 v38, v38
	v_sub_f32_e32 v39, v39, v49
	v_add_f32_e32 v48, v21, v48
	v_exp_f32_e32 v23, v23
	v_sub_f32_e32 v24, v24, v49
	v_add_f32_e32 v48, v37, v48
	v_exp_f32_e32 v39, v39
	v_sub_f32_e32 v40, v40, v49
	v_add_f32_e32 v48, v22, v48
	v_exp_f32_e32 v24, v24
	v_sub_f32_e32 v25, v25, v49
	v_add_f32_e32 v48, v38, v48
	v_exp_f32_e32 v40, v40
	v_sub_f32_e32 v41, v41, v49
	v_add_f32_e32 v48, v23, v48
	v_exp_f32_e32 v25, v25
	v_sub_f32_e32 v26, v26, v49
	v_add_f32_e32 v48, v39, v48
	v_exp_f32_e32 v41, v41
	v_sub_f32_e32 v42, v42, v49
	v_add_f32_e32 v48, v24, v48
	v_exp_f32_e32 v26, v26
	v_sub_f32_e32 v27, v27, v49
	v_add_f32_e32 v48, v40, v48
	v_exp_f32_e32 v42, v42
	v_sub_f32_e32 v43, v43, v49
	v_add_f32_e32 v48, v25, v48
	v_exp_f32_e32 v27, v27
	v_sub_f32_e32 v28, v28, v49
	v_add_f32_e32 v48, v41, v48
	v_exp_f32_e32 v43, v43
	v_sub_f32_e32 v44, v44, v49
	v_add_f32_e32 v48, v26, v48
	v_exp_f32_e32 v28, v28
	v_sub_f32_e32 v29, v29, v49
	v_add_f32_e32 v48, v42, v48
	v_exp_f32_e32 v44, v44
	v_sub_f32_e32 v45, v45, v49
	v_add_f32_e32 v48, v27, v48
	v_exp_f32_e32 v29, v29
	v_sub_f32_e32 v30, v30, v49
	v_add_f32_e32 v48, v43, v48
	v_exp_f32_e32 v45, v45
	v_sub_f32_e32 v46, v46, v49
	v_add_f32_e32 v48, v28, v48
	v_exp_f32_e32 v30, v30
	v_sub_f32_e32 v31, v31, v49
	v_add_f32_e32 v48, v44, v48
	v_exp_f32_e32 v46, v46
	v_sub_f32_e32 v47, v47, v49
	v_add_f32_e32 v48, v29, v48
	v_exp_f32_e32 v31, v31
	v_add_f32_e32 v48, v45, v48
	v_exp_f32_e32 v47, v47
	v_add_f32_e32 v48, v30, v48
	v_add_f32_e32 v48, v46, v48
	v_add_f32_e32 v48, v31, v48
	v_add_f32_e32 v48, v47, v48
	s_waitcnt vmcnt(3) lgkmcnt(0)
	s_barrier
; __device__ __forceinline__ float swap_max(float m) { auto rr = __builtin_amdgcn_permlane32_swap(__float_as_uint(m), __float_as_uint(m), false, false); return fmaxf(__uint_as_float(rr[0]), __uint_as_float(rr[1])); }
; #define DSR128(dst, addr, off) asm volatile("ds_read_b128 %0, %1 offset:%2" : "=&v"(dst) : "v"(addr), "i"(off))
; template <bool FIRST, bool HAS_PREV> ...
;     ...
;     { const float nm = FIRST ? 0.f : -st.mrun;
; #pragma unroll
;       for (int i = 0; i < 16; ++i) { c0[i] = nm; c1[i] = nm; } }
; #pragma unroll
;     for (int ks = 0; ks < 2; ++ks) { DSR128(kf[2 * ks], ka[ks], 0); DSR128(kf[2 * ks + 1], ka[ks], 4096); }
;     asm volatile("s_waitcnt lgkmcnt(0)" : "+v"(kf[0]), "+v"(kf[1]), "+v"(kf[2]), "+v"(kf[3]));
; #pragma unroll
;     for (int ks = 0; ks < 2; ++ks) {
;         c0 = __builtin_amdgcn_mfma_f32_32x32x16_bf16(kf[2 * ks], qr[ks], c0, 0, 0, 0);
;         c1 = __builtin_amdgcn_mfma_f32_32x32x16_bf16(kf[2 * ks + 1], qr[ks], c1, 0, 0, 0);
;     }
;     __builtin_amdgcn_sched_barrier(0);
;     { bf16x8 kg[4];
; #pragma unroll
;       for (int ks = 0; ks < 2; ++ks) { DSR128(kg[2 * ks], ka[2 + ks], 0); DSR128(kg[2 * ks + 1], ka[2 + ks], 4096); }
;       asm volatile("s_waitcnt lgkmcnt(0)" : "+v"(kg[0]), "+v"(kg[1]), "+v"(kg[2]), "+v"(kg[3]));
; #pragma unroll
;       for (int ks = 0; ks < 2; ++ks) {
;           c0 = __builtin_amdgcn_mfma_f32_32x32x16_bf16(kg[2 * ks], qr[2 + ks], c0, 0, 0, 0);
;           c1 = __builtin_amdgcn_mfma_f32_32x32x16_bf16(kg[2 * ks + 1], qr[2 + ks], c1, 0, 0, 0);
;       } }
;     __builtin_amdgcn_sched_barrier(0);
;     if (HAS_PREV) {
; #pragma unroll
;         for (int e = 0; e < 4; ++e) DSR128(vA[e], va[0], e * 4096);
;     }
;     float mx = fmaxf(c0[0], c1[0]);
; #pragma unroll
;     for (int i = 1; i < 16; ++i) mx = fmaxf(mx, fmaxf(c0[i], c1[i]));
;     mx = swap_max(mx);
;     float a = 1.0f;
;     { const float dl = FIRST ? mx : ((mx > 8.0f) ? mx : 0.f);
;       if (FIRST || __any(dl != 0.f)) {
; #pragma unroll
;           for (int i = 0; i < 16; ++i) { c0[i] -= dl; c1[i] -= dl; }
;           st.mrun += dl; if (!FIRST) a = __builtin_amdgcn_exp2f(-dl);
;       } }
	ds_read_b128 v[128:131], v209 offset:8192
	ds_read_b128 v[132:135], v209 offset:12288
	ds_read_b128 v[136:139], v211 offset:8192
	ds_read_b128 v[140:143], v211 offset:12288
	ds_read_b128 v[222:225], v213 offset:8192
	ds_read_b128 v[226:229], v213 offset:12288
	ds_read_b128 v[230:233], v215 offset:8192
	ds_read_b128 v[234:237], v215 offset:12288
	v_pk_add_f32 v[198:199], v[48:49], 0 op_sel_hi:[1,0]
	v_xor_b32_e32 v158, 0x80000000, v49
	v_mov_b32_e32 v159, v158
	v_mov_b32_e32 v160, v158
	v_mov_b32_e32 v161, v158
	v_mov_b32_e32 v162, v158
	v_mov_b32_e32 v163, v158
	v_mov_b32_e32 v164, v158
	v_mov_b32_e32 v165, v158
	v_mov_b32_e32 v166, v158
	v_mov_b32_e32 v167, v158
	v_mov_b32_e32 v168, v158
	v_mov_b32_e32 v169, v158
	v_mov_b32_e32 v170, v158
	v_mov_b32_e32 v171, v158
	v_mov_b32_e32 v172, v158
	v_mov_b32_e32 v173, v158
	v_add_u32_e32 v174, 0x6000, v210
	v_add_u32_e32 v175, 0x6000, v212
	v_add_u32_e32 v178, 0x6000, v214
	v_add_u32_e32 v179, 0x6000, v216
	v_cvt_pk_bf16_f32 v124, v16, v17
	v_cvt_pk_bf16_f32 v125, v18, v19
	v_cvt_pk_bf16_f32 v126, v20, v21
	v_cvt_pk_bf16_f32 v127, v22, v23
	v_cvt_pk_bf16_f32 v120, v24, v25
	v_cvt_pk_bf16_f32 v121, v26, v27
	v_cvt_pk_bf16_f32 v122, v28, v29
	v_cvt_pk_bf16_f32 v123, v30, v31
	v_cvt_pk_bf16_f32 v116, v32, v33
	v_cvt_pk_bf16_f32 v117, v34, v35
	v_cvt_pk_bf16_f32 v118, v36, v37
	v_cvt_pk_bf16_f32 v119, v38, v39
	v_cvt_pk_bf16_f32 v112, v40, v41
	v_cvt_pk_bf16_f32 v113, v42, v43
	v_cvt_pk_bf16_f32 v114, v44, v45
	v_cvt_pk_bf16_f32 v115, v46, v47
	v_mov_b64_e32 v[30:31], v[14:15]
	v_mov_b64_e32 v[46:47], v[14:15]
	v_mov_b64_e32 v[62:63], v[14:15]
	v_lshl_add_u64 v[200:201], v[194:195], 0, s[82:83]
	v_subrev_u32_e32 v193, s36, v194
	s_add_u32 s54, s36, s82
	s_addc_u32 s55, s37, s83
	v_subrev_u32_e32 v182, s30, v196
	s_mov_b32 s56, s30
	s_mov_b32 s57, s31
	v_add_u32_e32 v182, 0x23008000, v182
	v_add_u32_e32 v183, 0x2000, v182
	s_mov_b32 s44, 0
	s_mov_b32 s52, 2
	s_mov_b64 s[46:47], 0
	v_mov_b64_e32 v[28:29], v[12:13]
	v_mov_b64_e32 v[26:27], v[10:11]
	v_mov_b64_e32 v[24:25], v[8:9]
	v_mov_b64_e32 v[22:23], v[6:7]
	v_mov_b64_e32 v[20:21], v[4:5]
	v_mov_b64_e32 v[18:19], v[2:3]
	v_mov_b64_e32 v[16:17], v[0:1]
	v_mov_b64_e32 v[44:45], v[12:13]
	v_mov_b64_e32 v[42:43], v[10:11]
	v_mov_b64_e32 v[40:41], v[8:9]
	v_mov_b64_e32 v[38:39], v[6:7]
	v_mov_b64_e32 v[36:37], v[4:5]
	v_mov_b64_e32 v[34:35], v[2:3]
	v_mov_b64_e32 v[32:33], v[0:1]
	s_mov_b32 s53, 1
	v_mov_b64_e32 v[60:61], v[12:13]
	v_mov_b64_e32 v[58:59], v[10:11]
	v_mov_b64_e32 v[56:57], v[8:9]
	v_mov_b64_e32 v[54:55], v[6:7]
	v_mov_b64_e32 v[52:53], v[4:5]
	v_mov_b64_e32 v[50:51], v[2:3]
	v_mov_b64_e32 v[48:49], v[0:1]
.LBB0_561:
	s_mov_b32 s51, 0
	s_waitcnt lgkmcnt(4)
	v_mfma_f32_32x32x16_bf16 v[80:95], v[128:131], v[96:99], v[158:173]
	v_mfma_f32_32x32x16_bf16 v[64:79], v[132:135], v[96:99], v[158:173]
	v_mfma_f32_32x32x16_bf16 v[80:95], v[136:139], v[100:103], v[80:95]
	v_mfma_f32_32x32x16_bf16 v[64:79], v[140:143], v[100:103], v[64:79]
	s_waitcnt lgkmcnt(0)
	v_mfma_f32_32x32x16_bf16 v[80:95], v[222:225], v[104:107], v[80:95]
	v_mfma_f32_32x32x16_bf16 v[64:79], v[226:229], v[104:107], v[64:79]
	v_mfma_f32_32x32x16_bf16 v[80:95], v[230:233], v[108:111], v[80:95]
	v_mfma_f32_32x32x16_bf16 v[64:79], v[234:237], v[108:111], v[64:79]
	ds_read_b128 v[140:143], v174 offset:0
	ds_read_b128 v[136:139], v174 offset:4096
	ds_read_b128 v[132:135], v174 offset:8192
	ds_read_b128 v[128:131], v174 offset:12288
	s_nop 6
	v_max3_f32 v202, v80, v81, v82
	v_max3_f32 v202, v202, v83, v84
	v_max3_f32 v202, v202, v85, v86
	v_max3_f32 v202, v202, v87, v88
	v_max3_f32 v202, v202, v89, v90
	v_max3_f32 v202, v202, v91, v92
	v_max3_f32 v202, v202, v93, v94
	v_max3_f32 v204, v64, v65, v66
	v_max3_f32 v204, v204, v67, v68
	v_max3_f32 v204, v204, v69, v70
	v_max3_f32 v204, v204, v71, v72
	v_max3_f32 v204, v204, v73, v74
	v_max3_f32 v204, v204, v75, v76
	v_max3_f32 v204, v204, v77, v78
	v_max3_f32 v202, v202, v95, v79
	v_max_f32_e32 v202, v202, v204
	v_mov_b32_e32 v204, v202
	s_nop 1
	v_permlane32_swap_b32_e32 v202, v204
	v_max_f32_e32 v202, v202, v204
	v_cmp_lt_f32_e32 vcc, s84, v202
	s_cbranch_vccnz .Lu3_rare_1

; template <bool FIRST, bool HAS_PREV> ...
;     ...
;     { const float nm = FIRST ? 0.f : -st.mrun;
; #pragma unroll
;       for (int i = 0; i < 16; ++i) { c0[i] = nm; c1[i] = nm; } }
; #pragma unroll
;     for (int ks = 0; ks < 2; ++ks) { DSR128(kf[2 * ks], ka[ks], 0); DSR128(kf[2 * ks + 1], ka[ks], 4096); }
;     asm volatile("s_waitcnt lgkmcnt(0)" : "+v"(kf[0]), "+v"(kf[1]), "+v"(kf[2]), "+v"(kf[3]));
; #pragma unroll
;     for (int ks = 0; ks < 2; ++ks) {
;         c0 = __builtin_amdgcn_mfma_f32_32x32x16_bf16(kf[2 * ks], qr[ks], c0, 0, 0, 0);
;         c1 = __builtin_amdgcn_mfma_f32_32x32x16_bf16(kf[2 * ks + 1], qr[ks], c1, 0, 0, 0);
;     }
;     __builtin_amdgcn_sched_barrier(0);
;     { bf16x8 kg[4];
; #pragma unroll
;       for (int ks = 0; ks < 2; ++ks) { DSR128(kg[2 * ks], ka[2 + ks], 0); DSR128(kg[2 * ks + 1], ka[2 + ks], 4096); }
;       asm volatile("s_waitcnt lgkmcnt(0)" : "+v"(kg[0]), "+v"(kg[1]), "+v"(kg[2]), "+v"(kg[3]));
; #pragma unroll
;       for (int ks = 0; ks < 2; ++ks) {
;           c0 = __builtin_amdgcn_mfma_f32_32x32x16_bf16(kg[2 * ks], qr[2 + ks], c0, 0, 0, 0);
;           c1 = __builtin_amdgcn_mfma_f32_32x32x16_bf16(kg[2 * ks + 1], qr[2 + ks], c1, 0, 0, 0);
;       } }
;     __builtin_amdgcn_sched_barrier(0);
;     if (HAS_PREV) {
; #pragma unroll
;         for (int e = 0; e < 4; ++e) DSR128(vA[e], va[0], e * 4096);
;     }
;     float mx = fmaxf(c0[0], c1[0]);
; #pragma unroll
;     for (int i = 1; i < 16; ++i) mx = fmaxf(mx, fmaxf(c0[i], c1[i]));
;     mx = swap_max(mx);
;     ...
;     { u32x4 w;
;       w.x = pg8::cvt_pk_bf16(c0[0], c0[1]); w.y = pg8::cvt_pk_bf16(c0[2], c0[3]); w.z = pg8::cvt_pk_bf16(c0[4], c0[5]); w.w = pg8::cvt_pk_bf16(c0[6], c0[7]); pbp[0] = __builtin_bit_cast(bf16x8, w);
;       w.x = pg8::cvt_pk_bf16(c0[8], c0[9]); w.y = pg8::cvt_pk_bf16(c0[10], c0[11]); w.z = pg8::cvt_pk_bf16(c0[12], c0[13]); w.w = pg8::cvt_pk_bf16(c0[14], c0[15]); pbp[1] = __builtin_bit_cast(bf16x8, w);
;       w.x = pg8::cvt_pk_bf16(c1[0], c1[1]); w.y = pg8::cvt_pk_bf16(c1[2], c1[3]); w.z = pg8::cvt_pk_bf16(c1[4], c1[5]); w.w = pg8::cvt_pk_bf16(c1[6], c1[7]); pbp[2] = __builtin_bit_cast(bf16x8, w);
;       w.x = pg8::cvt_pk_bf16(c1[8], c1[9]); w.y = pg8::cvt_pk_bf16(c1[10], c1[11]); w.z = pg8::cvt_pk_bf16(c1[12], c1[13]); w.w = pg8::cvt_pk_bf16(c1[14], c1[15]); pbp[3] = __builtin_bit_cast(bf16x8, w); }
.Lu3_wd_1:
	s_barrier
	s_add_u32 s46, s46, 0x4000
	s_addc_u32 s47, s47, 0
	s_add_i32 s53, s53, 1
	s_add_u32 s54, s54, 0x10000
	s_addc_u32 s55, s55, 0
	s_add_u32 s56, s56, 0x4000
	s_addc_u32 s57, s57, 0
	s_cmp_eq_u32 s46, 0x7c000
	s_cbranch_scc1 .Lu3_exit
	ds_read_b128 v[128:131], v209 offset:16384
	ds_read_b128 v[132:135], v209 offset:20480
	ds_read_b128 v[136:139], v211 offset:16384
	ds_read_b128 v[140:143], v211 offset:20480
	ds_read_b128 v[222:225], v213 offset:16384
	ds_read_b128 v[226:229], v213 offset:20480
	ds_read_b128 v[230:233], v215 offset:16384
	ds_read_b128 v[234:237], v215 offset:20480
	v_cvt_pk_bf16_f32 v124, v80, v81
	v_cvt_pk_bf16_f32 v125, v82, v83
	v_cvt_pk_bf16_f32 v126, v84, v85
	v_cvt_pk_bf16_f32 v127, v86, v87
	v_cvt_pk_bf16_f32 v120, v88, v89
	v_cvt_pk_bf16_f32 v121, v90, v91
	v_cvt_pk_bf16_f32 v122, v92, v93
	v_cvt_pk_bf16_f32 v123, v94, v95
	v_cvt_pk_bf16_f32 v116, v64, v65
	v_cvt_pk_bf16_f32 v117, v66, v67
	v_cvt_pk_bf16_f32 v118, v68, v69
	v_cvt_pk_bf16_f32 v119, v70, v71
	v_cvt_pk_bf16_f32 v112, v72, v73
	v_cvt_pk_bf16_f32 v113, v74, v75
	v_cvt_pk_bf16_f32 v114, v76, v77
	v_cvt_pk_bf16_f32 v115, v78, v79
	s_mov_b32 s51, 0
	s_waitcnt lgkmcnt(4)
	v_mfma_f32_32x32x16_bf16 v[80:95], v[128:131], v[96:99], v[158:173]
	v_mfma_f32_32x32x16_bf16 v[64:79], v[132:135], v[96:99], v[158:173]
	v_mfma_f32_32x32x16_bf16 v[80:95], v[136:139], v[100:103], v[80:95]
	v_mfma_f32_32x32x16_bf16 v[64:79], v[140:143], v[100:103], v[64:79]
	s_waitcnt lgkmcnt(0)
	v_mfma_f32_32x32x16_bf16 v[80:95], v[222:225], v[104:107], v[80:95]
	v_mfma_f32_32x32x16_bf16 v[64:79], v[226:229], v[104:107], v[64:79]
	v_mfma_f32_32x32x16_bf16 v[80:95], v[230:233], v[108:111], v[80:95]
	v_mfma_f32_32x32x16_bf16 v[64:79], v[234:237], v[108:111], v[64:79]
	ds_read_b128 v[140:143], v174 offset:16384
	ds_read_b128 v[136:139], v174 offset:20480
	ds_read_b128 v[132:135], v174 offset:24576
	ds_read_b128 v[128:131], v174 offset:28672
	s_nop 6
	v_max3_f32 v202, v80, v81, v82
	v_max3_f32 v202, v202, v83, v84
	v_max3_f32 v202, v202, v85, v86
	v_max3_f32 v202, v202, v87, v88
	v_max3_f32 v202, v202, v89, v90
	v_max3_f32 v202, v202, v91, v92
	v_max3_f32 v202, v202, v93, v94
	v_max3_f32 v204, v64, v65, v66
	v_max3_f32 v204, v204, v67, v68
	v_max3_f32 v204, v204, v69, v70
	v_max3_f32 v204, v204, v71, v72
	v_max3_f32 v204, v204, v73, v74
	v_max3_f32 v204, v204, v75, v76
	v_max3_f32 v204, v204, v77, v78
	v_max3_f32 v202, v202, v95, v79
	v_max_f32_e32 v202, v202, v204
	v_mov_b32_e32 v204, v202
	s_nop 1
	v_permlane32_swap_b32_e32 v202, v204
	v_max_f32_e32 v202, v202, v204
	v_cmp_lt_f32_e32 vcc, s84, v202
	s_cbranch_vccnz .Lu3_rare_2

; template <bool FIRST, bool HAS_PREV> ...
;     ...
;     { const float nm = FIRST ? 0.f : -st.mrun;
; #pragma unroll
;       for (int i = 0; i < 16; ++i) { c0[i] = nm; c1[i] = nm; } }
; #pragma unroll
;     for (int ks = 0; ks < 2; ++ks) { DSR128(kf[2 * ks], ka[ks], 0); DSR128(kf[2 * ks + 1], ka[ks], 4096); }
;     asm volatile("s_waitcnt lgkmcnt(0)" : "+v"(kf[0]), "+v"(kf[1]), "+v"(kf[2]), "+v"(kf[3]));
; #pragma unroll
;     for (int ks = 0; ks < 2; ++ks) {
;         c0 = __builtin_amdgcn_mfma_f32_32x32x16_bf16(kf[2 * ks], qr[ks], c0, 0, 0, 0);
;         c1 = __builtin_amdgcn_mfma_f32_32x32x16_bf16(kf[2 * ks + 1], qr[ks], c1, 0, 0, 0);
;     }
;     __builtin_amdgcn_sched_barrier(0);
;     { bf16x8 kg[4];
; #pragma unroll
;       for (int ks = 0; ks < 2; ++ks) { DSR128(kg[2 * ks], ka[2 + ks], 0); DSR128(kg[2 * ks + 1], ka[2 + ks], 4096); }
;       asm volatile("s_waitcnt lgkmcnt(0)" : "+v"(kg[0]), "+v"(kg[1]), "+v"(kg[2]), "+v"(kg[3]));
; #pragma unroll
;       for (int ks = 0; ks < 2; ++ks) {
;           c0 = __builtin_amdgcn_mfma_f32_32x32x16_bf16(kg[2 * ks], qr[2 + ks], c0, 0, 0, 0);
;           c1 = __builtin_amdgcn_mfma_f32_32x32x16_bf16(kg[2 * ks + 1], qr[2 + ks], c1, 0, 0, 0);
;       } }
;     __builtin_amdgcn_sched_barrier(0);
;     if (HAS_PREV) {
; #pragma unroll
;         for (int e = 0; e < 4; ++e) DSR128(vA[e], va[0], e * 4096);
;     }
;     float mx = fmaxf(c0[0], c1[0]);
; #pragma unroll
;     for (int i = 1; i < 16; ++i) mx = fmaxf(mx, fmaxf(c0[i], c1[i]));
;     mx = swap_max(mx);
;     ...
;     { u32x4 w;
;       w.x = pg8::cvt_pk_bf16(c0[0], c0[1]); w.y = pg8::cvt_pk_bf16(c0[2], c0[3]); w.z = pg8::cvt_pk_bf16(c0[4], c0[5]); w.w = pg8::cvt_pk_bf16(c0[6], c0[7]); pbp[0] = __builtin_bit_cast(bf16x8, w);
;       w.x = pg8::cvt_pk_bf16(c0[8], c0[9]); w.y = pg8::cvt_pk_bf16(c0[10], c0[11]); w.z = pg8::cvt_pk_bf16(c0[12], c0[13]); w.w = pg8::cvt_pk_bf16(c0[14], c0[15]); pbp[1] = __builtin_bit_cast(bf16x8, w);
;       w.x = pg8::cvt_pk_bf16(c1[0], c1[1]); w.y = pg8::cvt_pk_bf16(c1[2], c1[3]); w.z = pg8::cvt_pk_bf16(c1[4], c1[5]); w.w = pg8::cvt_pk_bf16(c1[6], c1[7]); pbp[2] = __builtin_bit_cast(bf16x8, w);
;       w.x = pg8::cvt_pk_bf16(c1[8], c1[9]); w.y = pg8::cvt_pk_bf16(c1[10], c1[11]); w.z = pg8::cvt_pk_bf16(c1[12], c1[13]); w.w = pg8::cvt_pk_bf16(c1[14], c1[15]); pbp[3] = __builtin_bit_cast(bf16x8, w); }
.Lu3_wd_2:
	s_barrier
	s_add_u32 s46, s46, 0x4000
	s_addc_u32 s47, s47, 0
	s_add_i32 s53, s53, 1
	s_add_u32 s54, s54, 0x10000
	s_addc_u32 s55, s55, 0
	s_add_u32 s56, s56, 0x4000
	s_addc_u32 s57, s57, 0
	ds_read_b128 v[128:131], v209 offset:0
	ds_read_b128 v[132:135], v209 offset:4096
	ds_read_b128 v[136:139], v211 offset:0
	ds_read_b128 v[140:143], v211 offset:4096
	ds_read_b128 v[222:225], v213 offset:0
	ds_read_b128 v[226:229], v213 offset:4096
	ds_read_b128 v[230:233], v215 offset:0
	ds_read_b128 v[234:237], v215 offset:4096
	v_cvt_pk_bf16_f32 v124, v80, v81
	v_cvt_pk_bf16_f32 v125, v82, v83
	v_cvt_pk_bf16_f32 v126, v84, v85
	v_cvt_pk_bf16_f32 v127, v86, v87
	v_cvt_pk_bf16_f32 v120, v88, v89
	v_cvt_pk_bf16_f32 v121, v90, v91
	v_cvt_pk_bf16_f32 v122, v92, v93
	v_cvt_pk_bf16_f32 v123, v94, v95
	v_cvt_pk_bf16_f32 v116, v64, v65
	v_cvt_pk_bf16_f32 v117, v66, v67
	v_cvt_pk_bf16_f32 v118, v68, v69
	v_cvt_pk_bf16_f32 v119, v70, v71
	v_cvt_pk_bf16_f32 v112, v72, v73
	v_cvt_pk_bf16_f32 v113, v74, v75
	v_cvt_pk_bf16_f32 v114, v76, v77
	v_cvt_pk_bf16_f32 v115, v78, v79
	s_mov_b32 s51, 0
	s_waitcnt lgkmcnt(4)
	v_mfma_f32_32x32x16_bf16 v[80:95], v[128:131], v[96:99], v[158:173]
	v_mfma_f32_32x32x16_bf16 v[64:79], v[132:135], v[96:99], v[158:173]
	v_mfma_f32_32x32x16_bf16 v[80:95], v[136:139], v[100:103], v[80:95]
	v_mfma_f32_32x32x16_bf16 v[64:79], v[140:143], v[100:103], v[64:79]
	s_waitcnt lgkmcnt(0)
	v_mfma_f32_32x32x16_bf16 v[80:95], v[222:225], v[104:107], v[80:95]
	v_mfma_f32_32x32x16_bf16 v[64:79], v[226:229], v[104:107], v[64:79]
	v_mfma_f32_32x32x16_bf16 v[80:95], v[230:233], v[108:111], v[80:95]
	v_mfma_f32_32x32x16_bf16 v[64:79], v[234:237], v[108:111], v[64:79]
	ds_read_b128 v[140:143], v174 offset:32768
	ds_read_b128 v[136:139], v174 offset:36864
	ds_read_b128 v[132:135], v174 offset:40960
	ds_read_b128 v[128:131], v174 offset:45056
	s_nop 6
	v_max3_f32 v202, v80, v81, v82
	v_max3_f32 v202, v202, v83, v84
	v_max3_f32 v202, v202, v85, v86
	v_max3_f32 v202, v202, v87, v88
	v_max3_f32 v202, v202, v89, v90
	v_max3_f32 v202, v202, v91, v92
	v_max3_f32 v202, v202, v93, v94
	v_max3_f32 v204, v64, v65, v66
	v_max3_f32 v204, v204, v67, v68
	v_max3_f32 v204, v204, v69, v70
	v_max3_f32 v204, v204, v71, v72
	v_max3_f32 v204, v204, v73, v74
	v_max3_f32 v204, v204, v75, v76
	v_max3_f32 v204, v204, v77, v78
	v_max3_f32 v202, v202, v95, v79
	v_max_f32_e32 v202, v202, v204
	v_mov_b32_e32 v204, v202
	s_nop 1
	v_permlane32_swap_b32_e32 v202, v204
	v_max_f32_e32 v202, v202, v204
	v_cmp_lt_f32_e32 vcc, s84, v202
	s_cbranch_vccnz .Lu3_rare_0

; __device__ __forceinline__ unsigned cvt_pk_bf16(float lo, float hi) { cvt_f32x2_t v = {lo, hi}; cvt_bf16x2_t b = __builtin_convertvector(v, cvt_bf16x2_t); return __builtin_bit_cast(unsigned, b); }
; #define DSR128(dst, addr, off) asm volatile("ds_read_b128 %0, %1 offset:%2" : "=&v"(dst) : "v"(addr), "i"(off))
; template <bool FIRST, bool HAS_PREV> ...
;     ...
;     { const float nm = FIRST ? 0.f : -st.mrun;
; #pragma unroll
;       for (int i = 0; i < 16; ++i) { c0[i] = nm; c1[i] = nm; } }
; #pragma unroll
;     for (int ks = 0; ks < 2; ++ks) { DSR128(kf[2 * ks], ka[ks], 0); DSR128(kf[2 * ks + 1], ka[ks], 4096); }
;     asm volatile("s_waitcnt lgkmcnt(0)" : "+v"(kf[0]), "+v"(kf[1]), "+v"(kf[2]), "+v"(kf[3]));
; #pragma unroll
;     for (int ks = 0; ks < 2; ++ks) {
;         c0 = __builtin_amdgcn_mfma_f32_32x32x16_bf16(kf[2 * ks], qr[ks], c0, 0, 0, 0);
;         c1 = __builtin_amdgcn_mfma_f32_32x32x16_bf16(kf[2 * ks + 1], qr[ks], c1, 0, 0, 0);
;     }
;     __builtin_amdgcn_sched_barrier(0);
;     { bf16x8 kg[4];
; #pragma unroll
;       for (int ks = 0; ks < 2; ++ks) { DSR128(kg[2 * ks], ka[2 + ks], 0); DSR128(kg[2 * ks + 1], ka[2 + ks], 4096); }
;       asm volatile("s_waitcnt lgkmcnt(0)" : "+v"(kg[0]), "+v"(kg[1]), "+v"(kg[2]), "+v"(kg[3]));
;     ...
;     { u32x4 w;
;       w.x = pg8::cvt_pk_bf16(c0[0], c0[1]); w.y = pg8::cvt_pk_bf16(c0[2], c0[3]); w.z = pg8::cvt_pk_bf16(c0[4], c0[5]); w.w = pg8::cvt_pk_bf16(c0[6], c0[7]); pbp[0] = __builtin_bit_cast(bf16x8, w);
;       w.x = pg8::cvt_pk_bf16(c0[8], c0[9]); w.y = pg8::cvt_pk_bf16(c0[10], c0[11]); w.z = pg8::cvt_pk_bf16(c0[12], c0[13]); w.w = pg8::cvt_pk_bf16(c0[14], c0[15]); pbp[1] = __builtin_bit_cast(bf16x8, w);
;       w.x = pg8::cvt_pk_bf16(c1[0], c1[1]); w.y = pg8::cvt_pk_bf16(c1[2], c1[3]); w.z = pg8::cvt_pk_bf16(c1[4], c1[5]); w.w = pg8::cvt_pk_bf16(c1[6], c1[7]); pbp[2] = __builtin_bit_cast(bf16x8, w);
;       w.x = pg8::cvt_pk_bf16(c1[8], c1[9]); w.y = pg8::cvt_pk_bf16(c1[10], c1[11]); w.z = pg8::cvt_pk_bf16(c1[12], c1[13]); w.w = pg8::cvt_pk_bf16(c1[14], c1[15]); pbp[3] = __builtin_bit_cast(bf16x8, w); }
.Lu3_wd_0:
	s_barrier
	s_add_u32 s46, s46, 0x4000
	s_addc_u32 s47, s47, 0
	s_add_i32 s53, s53, 1
	s_add_u32 s54, s54, 0x10000
	s_addc_u32 s55, s55, 0
	s_add_u32 s56, s56, 0x4000
	s_addc_u32 s57, s57, 0
	ds_read_b128 v[128:131], v209 offset:8192
	ds_read_b128 v[132:135], v209 offset:12288
	ds_read_b128 v[136:139], v211 offset:8192
	ds_read_b128 v[140:143], v211 offset:12288
	ds_read_b128 v[222:225], v213 offset:8192
	ds_read_b128 v[226:229], v213 offset:12288
	ds_read_b128 v[230:233], v215 offset:8192
	ds_read_b128 v[234:237], v215 offset:12288
	v_cvt_pk_bf16_f32 v124, v80, v81
	v_cvt_pk_bf16_f32 v125, v82, v83
	v_cvt_pk_bf16_f32 v126, v84, v85
	v_cvt_pk_bf16_f32 v127, v86, v87
	v_cvt_pk_bf16_f32 v120, v88, v89
	v_cvt_pk_bf16_f32 v121, v90, v91
	v_cvt_pk_bf16_f32 v122, v92, v93
	v_cvt_pk_bf16_f32 v123, v94, v95
	v_cvt_pk_bf16_f32 v116, v64, v65
	v_cvt_pk_bf16_f32 v117, v66, v67
	v_cvt_pk_bf16_f32 v118, v68, v69
	v_cvt_pk_bf16_f32 v119, v70, v71
	v_cvt_pk_bf16_f32 v112, v72, v73
	v_cvt_pk_bf16_f32 v113, v74, v75
	v_cvt_pk_bf16_f32 v114, v76, v77
	v_cvt_pk_bf16_f32 v115, v78, v79
	s_branch .LBB0_561

; __device__ __forceinline__ unsigned cvt_pk_bf16(float lo, float hi) { cvt_f32x2_t v = {lo, hi}; cvt_bf16x2_t b = __builtin_convertvector(v, cvt_bf16x2_t); return __builtin_bit_cast(unsigned, b); }
; #define LAS __attribute__((address_space(3)))
; template <bool FIRST, bool HAS_PREV> ...
;     ...
;     { u32x4 w;
;       w.x = pg8::cvt_pk_bf16(c0[0], c0[1]); w.y = pg8::cvt_pk_bf16(c0[2], c0[3]); w.z = pg8::cvt_pk_bf16(c0[4], c0[5]); w.w = pg8::cvt_pk_bf16(c0[6], c0[7]); pbp[0] = __builtin_bit_cast(bf16x8, w);
;       w.x = pg8::cvt_pk_bf16(c0[8], c0[9]); w.y = pg8::cvt_pk_bf16(c0[10], c0[11]); w.z = pg8::cvt_pk_bf16(c0[12], c0[13]); w.w = pg8::cvt_pk_bf16(c0[14], c0[15]); pbp[1] = __builtin_bit_cast(bf16x8, w);
;       w.x = pg8::cvt_pk_bf16(c1[0], c1[1]); w.y = pg8::cvt_pk_bf16(c1[2], c1[3]); w.z = pg8::cvt_pk_bf16(c1[4], c1[5]); w.w = pg8::cvt_pk_bf16(c1[6], c1[7]); pbp[2] = __builtin_bit_cast(bf16x8, w);
;       w.x = pg8::cvt_pk_bf16(c1[8], c1[9]); w.y = pg8::cvt_pk_bf16(c1[10], c1[11]); w.z = pg8::cvt_pk_bf16(c1[12], c1[13]); w.w = pg8::cvt_pk_bf16(c1[14], c1[15]); pbp[3] = __builtin_bit_cast(bf16x8, w); }
; __device__ __forceinline__ void attn_unit(LAS unsigned char* lds, const bf16* __restrict__ Qb, const bf16* __restrict__ Kb, const bf16* __restrict__ VT, bf16* __restrict__ Y,
;                                           const float* __restrict__ gsub, float lam, int b, int h, int qb, float* o1scr) {
;     ...
;         { const LAS unsigned char* vb = lds + VB0 + 1 * VSL;
; #pragma unroll
;           for (int e = 0; e < 4; ++e)
; #pragma unroll
;               for (int kk = 0; kk < 4; ++kk) { const bf16x8 vf = *(const LAS bf16x8*)(vb + e * 4096 + vofs[kk]);
;                   o[e] = __builtin_amdgcn_mfma_f32_32x32x16_bf16(vf, pbp[kk], o[e], 0, 0, 0); } }
.Lu3_exit:
	v_cvt_pk_bf16_f32 v124, v80, v81
	v_cvt_pk_bf16_f32 v125, v82, v83
	v_cvt_pk_bf16_f32 v126, v84, v85
	v_cvt_pk_bf16_f32 v127, v86, v87
	v_cvt_pk_bf16_f32 v120, v88, v89
	v_cvt_pk_bf16_f32 v121, v90, v91
	v_cvt_pk_bf16_f32 v122, v92, v93
	v_cvt_pk_bf16_f32 v123, v94, v95
	v_cvt_pk_bf16_f32 v116, v64, v65
	v_cvt_pk_bf16_f32 v117, v66, v67
	v_cvt_pk_bf16_f32 v118, v68, v69
	v_cvt_pk_bf16_f32 v119, v70, v71
	v_cvt_pk_bf16_f32 v112, v72, v73
	v_cvt_pk_bf16_f32 v113, v74, v75
	v_cvt_pk_bf16_f32 v114, v76, v77
	v_cvt_pk_bf16_f32 v115, v78, v79
	v_mov_b32_e32 v128, v198
